# DSA collect pass fast path: SIMD-style score evaluation, take/candidate decisions as 0/1 increments, 8 returning LDS atomics per half tile behind one wait
# baseline (speedup 1.0000x reference)
; __device__ __forceinline__ void dsa_item(const KP& p, int b, int tile, char* smem) {
;     ...
;     for (int kt = wid; kt < nkt; kt += 4) {
;       h8 ca[2];
; #pragma unroll
;       for (int i = 0; i < 2; ++i) ca[i] = na[i];
;       loadk(kt + 4 < nkt ? kt + 4 : kt, na);
;       float sc[8];
;       scores(ca, sc);
; #pragma unroll
;       for (int q = 0; q < 8; ++q) {
;         const int key = kt * 32 + (q >> 2) * 16 + 4 * hq + (q & 3);
;         if (key <= myt) {
;           const uint32_t u32 = skey(sc[q]);
;           bool take, isc = false;
;           if (st0 == 0) take = (((unsigned long long)u32 << 16) | (unsigned long long)(8191 - key)) >= mytk;
;           else {
;             const uint32_t p16 = u32 >> 16;
;             take = p16 > (uint32_t)myp16;
;             isc = p16 == (uint32_t)myp16;
;           }
;           if (take) {
;             const int pos = atomicAdd(&cnt[mytok], 1);
;             if (pos < 256) sel[mytok * 256 + pos] = (unsigned short)key;
;           } else if (isc) {
;             const int pos = atomicAdd(&ccnt[mytok], 1);
;             if (pos < DSA_CAP) cand[mytok * 128 + pos] = ((unsigned long long)u32 << 16) | (unsigned long long)(8191 - key);
;           }
;         }
.LBB0_1081:
	s_waitcnt vmcnt(0)
	v_mov_b64_e32 v[88:89], v[48:49]
	v_mov_b64_e32 v[86:87], v[46:47]
	v_mfma_f32_16x16x32_f16 v[54:57], v[50:53], v[38:41], 0
	v_mov_b32_e32 v0, v162
	v_add_u32_e32 v162, 4, v0
	v_cmp_gt_i32_e32 vcc, s68, v162
	v_mfma_f32_16x16x32_f16 v[46:49], v[86:89], v[38:41], 0
	v_mov_b32_e32 v127, v1
	v_cndmask_b32_e32 v0, v0, v162, vcc
	v_lshl_or_b32 v0, v0, 5, v157
	v_mfma_f32_16x16x32_f16 v[90:93], v[50:53], v[34:37], v[54:57]
	v_cmp_le_i32_e64 s[60:61], v160, v133
	v_mfma_f32_16x16x32_f16 v[54:57], v[86:89], v[34:37], v[46:49]
	s_nop 2
	v_mov_b64_e32 v[46:47], s[78:79]
	v_mad_i64_i32 v[48:49], s[2:3], v0, s5, v[46:47]
	v_lshl_add_u64 v[48:49], v[48:49], 0, v[126:127]
	v_or_b32_e32 v0, 16, v0
	v_add_co_u32_e32 v48, vcc, s23, v48
	v_mad_i64_i32 v[46:47], s[2:3], v0, s5, v[46:47]
	s_nop 0
	v_addc_co_u32_e32 v49, vcc, 0, v49, vcc
	v_lshl_add_u64 v[46:47], v[46:47], 0, v[126:127]
	v_add_co_u32_e32 v46, vcc, s23, v46
	v_mfma_f32_16x16x32_f16 v[94:97], v[50:53], v[26:29], 0
	s_nop 0
	v_addc_co_u32_e32 v47, vcc, 0, v47, vcc
	v_cmp_le_i32_e32 vcc, s68, v162
	v_mfma_f32_16x16x32_f16 v[98:101], v[50:53], v[2:5], 0
	v_mfma_f32_16x16x32_f16 v[102:105], v[50:53], v[6:9], 0
	v_mfma_f32_16x16x32_f16 v[106:109], v[50:53], v[10:13], 0
	v_mfma_f32_16x16x32_f16 v[110:113], v[50:53], v[14:17], 0
	v_mfma_f32_16x16x32_f16 v[114:117], v[50:53], v[18:21], 0
	v_mfma_f32_16x16x32_f16 v[118:121], v[50:53], v[22:25], 0
	v_mfma_f32_16x16x32_f16 v[122:125], v[50:53], v[30:33], 0
	global_load_dwordx4 v[50:53], v[48:49], off offset:2304
	s_nop 0
	global_load_dwordx4 v[46:49], v[46:47], off offset:2304
	v_mfma_f32_16x16x32_f16 v[58:61], v[86:89], v[26:29], 0
	v_mfma_f32_16x16x32_f16 v[62:65], v[86:89], v[2:5], 0
	v_mfma_f32_16x16x32_f16 v[66:69], v[86:89], v[6:9], 0
	v_mfma_f32_16x16x32_f16 v[70:73], v[86:89], v[10:13], 0
	v_mfma_f32_16x16x32_f16 v[74:77], v[86:89], v[14:17], 0
	v_mfma_f32_16x16x32_f16 v[78:81], v[86:89], v[18:21], 0
	v_mfma_f32_16x16x32_f16 v[82:85], v[86:89], v[22:25], 0
	v_mfma_f32_16x16x32_f16 v[86:89], v[86:89], v[30:33], 0
	s_xor_b64 s[14:15], s[46:47], exec
	s_cmp_lg_u64 s[14:15], 0
	s_cbranch_scc1 .Lcf_slow
	s_mov_b64 s[2:3], exec
	s_and_b64 s[14:15], exec, vcc
	s_or_b64 s[96:97], s[14:15], s[96:97]
	v_sub_u32_e32 v166, v133, v160
	v_fma_f32 v194, |v94|, v128, v90
	v_fma_f32 v195, |v95|, v128, v91
	v_fma_f32 v196, |v96|, v128, v92
	v_fma_f32 v197, |v97|, v128, v93
	v_fma_f32 v194, |v98|, v130, v194
	v_fma_f32 v195, |v99|, v130, v195
	v_fma_f32 v196, |v100|, v130, v196
	v_fma_f32 v197, |v101|, v130, v197
	v_fma_f32 v194, |v102|, v132, v194
	v_fma_f32 v195, |v103|, v132, v195
	v_fma_f32 v196, |v104|, v132, v196
	v_fma_f32 v197, |v105|, v132, v197
	v_fma_f32 v194, |v106|, v134, v194
	v_fma_f32 v195, |v107|, v134, v195
	v_fma_f32 v196, |v108|, v134, v196
	v_fma_f32 v197, |v109|, v134, v197
	v_fma_f32 v194, |v110|, v136, v194
	v_fma_f32 v195, |v111|, v136, v195
	v_fma_f32 v196, |v112|, v136, v196
	v_fma_f32 v197, |v113|, v136, v197
	v_fma_f32 v194, |v114|, v138, v194
	v_fma_f32 v195, |v115|, v138, v195
	v_fma_f32 v196, |v116|, v138, v196
	v_fma_f32 v197, |v117|, v138, v197
	v_fma_f32 v194, |v118|, v140, v194
	v_fma_f32 v195, |v119|, v140, v195
	v_fma_f32 v196, |v120|, v140, v196
	v_fma_f32 v197, |v121|, v140, v197
	v_fma_f32 v194, |v122|, v142, v194
	v_fma_f32 v195, |v123|, v142, v195
	v_fma_f32 v196, |v124|, v142, v196
	v_fma_f32 v197, |v125|, v142, v197
	v_add_f32_e32 v194, 0, v194
	v_add_f32_e32 v195, 0, v195
	v_add_f32_e32 v196, 0, v196
	v_add_f32_e32 v197, 0, v197
	v_ashrrev_i32_e32 v198, 31, v194
	v_ashrrev_i32_e32 v199, 31, v195
	v_ashrrev_i32_e32 v200, 31, v196
	v_ashrrev_i32_e32 v201, 31, v197
	v_or_b32_e32 v198, 0x80000000, v198
	v_or_b32_e32 v199, 0x80000000, v199
	v_or_b32_e32 v200, 0x80000000, v200
	v_or_b32_e32 v201, 0x80000000, v201
	v_xor_b32_e32 v202, v194, v198
	v_xor_b32_e32 v203, v195, v199
	v_xor_b32_e32 v204, v196, v200
	v_xor_b32_e32 v205, v197, v201
	v_cmp_ge_i32_e64 s[60:61], v166, 0
	v_cmp_gt_u32_sdwa s[30:31], v202, v42 src0_sel:WORD_1 src1_sel:DWORD
	v_cmp_eq_u32_sdwa s[66:67], v202, v42 src0_sel:WORD_1 src1_sel:DWORD
	s_and_b64 s[30:31], s[30:31], s[60:61]
	s_and_b64 s[66:67], s[66:67], s[60:61]
	v_cndmask_b32_e64 v206, 0, 1, s[30:31]
	v_cndmask_b32_e64 v210, 0, 1, s[66:67]
	v_cmp_ge_i32_e64 s[60:61], v166, 1
	v_cmp_gt_u32_sdwa s[30:31], v203, v42 src0_sel:WORD_1 src1_sel:DWORD
	v_cmp_eq_u32_sdwa s[66:67], v203, v42 src0_sel:WORD_1 src1_sel:DWORD
	s_and_b64 s[30:31], s[30:31], s[60:61]
	s_and_b64 s[66:67], s[66:67], s[60:61]
	v_cndmask_b32_e64 v207, 0, 1, s[30:31]
	v_cndmask_b32_e64 v211, 0, 1, s[66:67]
	v_cmp_ge_i32_e64 s[60:61], v166, 2
	v_cmp_gt_u32_sdwa s[30:31], v204, v42 src0_sel:WORD_1 src1_sel:DWORD
	v_cmp_eq_u32_sdwa s[66:67], v204, v42 src0_sel:WORD_1 src1_sel:DWORD
	s_and_b64 s[30:31], s[30:31], s[60:61]
	s_and_b64 s[66:67], s[66:67], s[60:61]
	v_cndmask_b32_e64 v208, 0, 1, s[30:31]
	v_cndmask_b32_e64 v212, 0, 1, s[66:67]
	v_cmp_ge_i32_e64 s[60:61], v166, 3
	v_cmp_gt_u32_sdwa s[30:31], v205, v42 src0_sel:WORD_1 src1_sel:DWORD
	v_cmp_eq_u32_sdwa s[66:67], v205, v42 src0_sel:WORD_1 src1_sel:DWORD
	s_and_b64 s[30:31], s[30:31], s[60:61]
	s_and_b64 s[66:67], s[66:67], s[60:61]
	v_cndmask_b32_e64 v209, 0, 1, s[30:31]
	v_cndmask_b32_e64 v213, 0, 1, s[66:67]
	ds_add_rtn_u32 v214, v145, v206 offset:41344
	ds_add_rtn_u32 v215, v145, v207 offset:41344
	ds_add_rtn_u32 v216, v145, v208 offset:41344
	ds_add_rtn_u32 v217, v145, v209 offset:41344
	ds_add_rtn_u32 v218, v145, v210 offset:41408
	ds_add_rtn_u32 v219, v145, v211 offset:41408
	ds_add_rtn_u32 v220, v145, v212 offset:41408
	ds_add_rtn_u32 v221, v145, v213 offset:41408
	v_lshlrev_b32_e32 v198, 8, v206
	v_lshlrev_b32_e32 v199, 8, v207
	v_lshlrev_b32_e32 v200, 8, v208
	v_lshlrev_b32_e32 v201, 8, v209
	v_lshlrev_b32_e32 v194, 7, v210
	v_lshlrev_b32_e32 v195, 7, v211
	v_lshlrev_b32_e32 v196, 7, v212
	v_lshlrev_b32_e32 v197, 7, v213
	s_waitcnt lgkmcnt(0)
	v_cmp_lt_u32_e32 vcc, v214, v198
	v_lshl_add_u32 v167, v214, 1, v43
	s_mov_b64 exec, vcc
	ds_write_b16 v167, v160 offset:32768
	s_mov_b64 exec, s[2:3]
	v_cmp_lt_u32_e32 vcc, v215, v199
	v_lshl_add_u32 v167, v215, 1, v43
	v_add_u32_e32 v168, 1, v160
	s_mov_b64 exec, vcc
	ds_write_b16 v167, v168 offset:32768
	s_mov_b64 exec, s[2:3]
	v_cmp_lt_u32_e32 vcc, v216, v200
	v_lshl_add_u32 v167, v216, 1, v43
	v_add_u32_e32 v168, 2, v160
	s_mov_b64 exec, vcc
	ds_write_b16 v167, v168 offset:32768
	s_mov_b64 exec, s[2:3]
	v_cmp_lt_u32_e32 vcc, v217, v201
	v_lshl_add_u32 v167, v217, 1, v43
	v_add_u32_e32 v168, 3, v160
	s_mov_b64 exec, vcc
	ds_write_b16 v167, v168 offset:32768
	s_mov_b64 exec, s[2:3]
	v_cmp_lt_u32_e32 vcc, v218, v194
	s_mov_b64 exec, vcc
	s_cbranch_execz .Lcf_nc00
	v_lshrrev_b32_e32 v223, 16, v202
	v_mov_b32_e32 v169, v161
	v_lshl_or_b32 v222, v202, 16, v169
	v_lshl_add_u32 v167, v218, 3, v147
	ds_write_b64 v167, v[222:223] offset:16384
; __device__ __forceinline__ void dsa_item(const KP& p, int b, int tile, char* smem) {
;     ...
; #pragma unroll
;       for (int q = 0; q < 8; ++q) {
;         const int key = kt * 32 + (q >> 2) * 16 + 4 * hq + (q & 3);
;         if (key <= myt) {
;           const uint32_t u32 = skey(sc[q]);
;           bool take, isc = false;
;           if (st0 == 0) take = (((unsigned long long)u32 << 16) | (unsigned long long)(8191 - key)) >= mytk;
;           else {
;             const uint32_t p16 = u32 >> 16;
;             take = p16 > (uint32_t)myp16;
;             isc = p16 == (uint32_t)myp16;
;           }
;           if (take) {
;             const int pos = atomicAdd(&cnt[mytok], 1);
;             if (pos < 256) sel[mytok * 256 + pos] = (unsigned short)key;
;           } else if (isc) {
;             const int pos = atomicAdd(&ccnt[mytok], 1);
;             if (pos < DSA_CAP) cand[mytok * 128 + pos] = ((unsigned long long)u32 << 16) | (unsigned long long)(8191 - key);
;           }
;         }
.Lcf_nc00:
	s_mov_b64 exec, s[2:3]
	v_cmp_lt_u32_e32 vcc, v219, v195
	s_mov_b64 exec, vcc
	s_cbranch_execz .Lcf_nc01
	v_lshrrev_b32_e32 v223, 16, v203
	v_subrev_u32_e32 v169, 1, v161
	v_lshl_or_b32 v222, v203, 16, v169
	v_lshl_add_u32 v167, v219, 3, v147
	ds_write_b64 v167, v[222:223] offset:16384
.Lcf_nc01:
	s_mov_b64 exec, s[2:3]
	v_cmp_lt_u32_e32 vcc, v220, v196
	s_mov_b64 exec, vcc
	s_cbranch_execz .Lcf_nc02
	v_lshrrev_b32_e32 v223, 16, v204
	v_subrev_u32_e32 v169, 2, v161
	v_lshl_or_b32 v222, v204, 16, v169
	v_lshl_add_u32 v167, v220, 3, v147
	ds_write_b64 v167, v[222:223] offset:16384
.Lcf_nc02:
	s_mov_b64 exec, s[2:3]
	v_cmp_lt_u32_e32 vcc, v221, v197
	s_mov_b64 exec, vcc
	s_cbranch_execz .Lcf_nc03
	v_lshrrev_b32_e32 v223, 16, v205
	v_subrev_u32_e32 v169, 3, v161
	v_lshl_or_b32 v222, v205, 16, v169
	v_lshl_add_u32 v167, v221, 3, v147
	ds_write_b64 v167, v[222:223] offset:16384
.Lcf_nc03:
	s_mov_b64 exec, s[2:3]
	v_fma_f32 v194, |v58|, v128, v54
	v_fma_f32 v195, |v59|, v128, v55
	v_fma_f32 v196, |v60|, v128, v56
	v_fma_f32 v197, |v61|, v128, v57
	v_fma_f32 v194, |v62|, v130, v194
	v_fma_f32 v195, |v63|, v130, v195
	v_fma_f32 v196, |v64|, v130, v196
	v_fma_f32 v197, |v65|, v130, v197
	v_fma_f32 v194, |v66|, v132, v194
	v_fma_f32 v195, |v67|, v132, v195
	v_fma_f32 v196, |v68|, v132, v196
	v_fma_f32 v197, |v69|, v132, v197
	v_fma_f32 v194, |v70|, v134, v194
	v_fma_f32 v195, |v71|, v134, v195
	v_fma_f32 v196, |v72|, v134, v196
	v_fma_f32 v197, |v73|, v134, v197
	v_fma_f32 v194, |v74|, v136, v194
	v_fma_f32 v195, |v75|, v136, v195
	v_fma_f32 v196, |v76|, v136, v196
	v_fma_f32 v197, |v77|, v136, v197
	v_fma_f32 v194, |v78|, v138, v194
	v_fma_f32 v195, |v79|, v138, v195
	v_fma_f32 v196, |v80|, v138, v196
	v_fma_f32 v197, |v81|, v138, v197
	v_fma_f32 v194, |v82|, v140, v194
	v_fma_f32 v195, |v83|, v140, v195
	v_fma_f32 v196, |v84|, v140, v196
	v_fma_f32 v197, |v85|, v140, v197
	v_fma_f32 v194, |v86|, v142, v194
	v_fma_f32 v195, |v87|, v142, v195
	v_fma_f32 v196, |v88|, v142, v196
	v_fma_f32 v197, |v89|, v142, v197
	v_add_f32_e32 v194, 0, v194
	v_add_f32_e32 v195, 0, v195
	v_add_f32_e32 v196, 0, v196
	v_add_f32_e32 v197, 0, v197
	v_ashrrev_i32_e32 v198, 31, v194
	v_ashrrev_i32_e32 v199, 31, v195
	v_ashrrev_i32_e32 v200, 31, v196
	v_ashrrev_i32_e32 v201, 31, v197
	v_or_b32_e32 v198, 0x80000000, v198
	v_or_b32_e32 v199, 0x80000000, v199
	v_or_b32_e32 v200, 0x80000000, v200
	v_or_b32_e32 v201, 0x80000000, v201
	v_xor_b32_e32 v202, v194, v198
	v_xor_b32_e32 v203, v195, v199
	v_xor_b32_e32 v204, v196, v200
	v_xor_b32_e32 v205, v197, v201
	v_cmp_ge_i32_e64 s[60:61], v166, 16
	v_cmp_gt_u32_sdwa s[30:31], v202, v42 src0_sel:WORD_1 src1_sel:DWORD
	v_cmp_eq_u32_sdwa s[66:67], v202, v42 src0_sel:WORD_1 src1_sel:DWORD
	s_and_b64 s[30:31], s[30:31], s[60:61]
	s_and_b64 s[66:67], s[66:67], s[60:61]
	v_cndmask_b32_e64 v206, 0, 1, s[30:31]
	v_cndmask_b32_e64 v210, 0, 1, s[66:67]
	v_cmp_ge_i32_e64 s[60:61], v166, 17
	v_cmp_gt_u32_sdwa s[30:31], v203, v42 src0_sel:WORD_1 src1_sel:DWORD
	v_cmp_eq_u32_sdwa s[66:67], v203, v42 src0_sel:WORD_1 src1_sel:DWORD
	s_and_b64 s[30:31], s[30:31], s[60:61]
	s_and_b64 s[66:67], s[66:67], s[60:61]
	v_cndmask_b32_e64 v207, 0, 1, s[30:31]
	v_cndmask_b32_e64 v211, 0, 1, s[66:67]
	v_cmp_ge_i32_e64 s[60:61], v166, 18
	v_cmp_gt_u32_sdwa s[30:31], v204, v42 src0_sel:WORD_1 src1_sel:DWORD
	v_cmp_eq_u32_sdwa s[66:67], v204, v42 src0_sel:WORD_1 src1_sel:DWORD
	s_and_b64 s[30:31], s[30:31], s[60:61]
	s_and_b64 s[66:67], s[66:67], s[60:61]
	v_cndmask_b32_e64 v208, 0, 1, s[30:31]
	v_cndmask_b32_e64 v212, 0, 1, s[66:67]
	v_cmp_ge_i32_e64 s[60:61], v166, 19
	v_cmp_gt_u32_sdwa s[30:31], v205, v42 src0_sel:WORD_1 src1_sel:DWORD
	v_cmp_eq_u32_sdwa s[66:67], v205, v42 src0_sel:WORD_1 src1_sel:DWORD
	s_and_b64 s[30:31], s[30:31], s[60:61]
	s_and_b64 s[66:67], s[66:67], s[60:61]
	v_cndmask_b32_e64 v209, 0, 1, s[30:31]
	v_cndmask_b32_e64 v213, 0, 1, s[66:67]
	ds_add_rtn_u32 v214, v145, v206 offset:41344
	ds_add_rtn_u32 v215, v145, v207 offset:41344
	ds_add_rtn_u32 v216, v145, v208 offset:41344
	ds_add_rtn_u32 v217, v145, v209 offset:41344
	ds_add_rtn_u32 v218, v145, v210 offset:41408
	ds_add_rtn_u32 v219, v145, v211 offset:41408
	ds_add_rtn_u32 v220, v145, v212 offset:41408
	ds_add_rtn_u32 v221, v145, v213 offset:41408
	v_lshlrev_b32_e32 v198, 8, v206
	v_lshlrev_b32_e32 v199, 8, v207
	v_lshlrev_b32_e32 v200, 8, v208
	v_lshlrev_b32_e32 v201, 8, v209
	v_lshlrev_b32_e32 v194, 7, v210
	v_lshlrev_b32_e32 v195, 7, v211
	v_lshlrev_b32_e32 v196, 7, v212
	v_lshlrev_b32_e32 v197, 7, v213
	s_waitcnt lgkmcnt(0)
	v_cmp_lt_u32_e32 vcc, v214, v198
	v_lshl_add_u32 v167, v214, 1, v43
	v_add_u32_e32 v168, 16, v160
	s_mov_b64 exec, vcc
	ds_write_b16 v167, v168 offset:32768
	s_mov_b64 exec, s[2:3]
	v_cmp_lt_u32_e32 vcc, v215, v199
	v_lshl_add_u32 v167, v215, 1, v43
	v_add_u32_e32 v168, 17, v160
	s_mov_b64 exec, vcc
	ds_write_b16 v167, v168 offset:32768
	s_mov_b64 exec, s[2:3]
	v_cmp_lt_u32_e32 vcc, v216, v200
	v_lshl_add_u32 v167, v216, 1, v43
	v_add_u32_e32 v168, 18, v160
	s_mov_b64 exec, vcc
	ds_write_b16 v167, v168 offset:32768
	s_mov_b64 exec, s[2:3]
	v_cmp_lt_u32_e32 vcc, v217, v201
	v_lshl_add_u32 v167, v217, 1, v43
	v_add_u32_e32 v168, 19, v160
	s_mov_b64 exec, vcc
	ds_write_b16 v167, v168 offset:32768
	s_mov_b64 exec, s[2:3]
	v_cmp_lt_u32_e32 vcc, v218, v194
	s_mov_b64 exec, vcc
	s_cbranch_execz .Lcf_nc10
	v_lshrrev_b32_e32 v223, 16, v202
	v_subrev_u32_e32 v169, 16, v161
	v_lshl_or_b32 v222, v202, 16, v169
	v_lshl_add_u32 v167, v218, 3, v147
	ds_write_b64 v167, v[222:223] offset:16384
; __device__ __forceinline__ void dsa_item(const KP& p, int b, int tile, char* smem) {
;     ...
; #pragma unroll
;       for (int q = 0; q < 8; ++q) {
;         const int key = kt * 32 + (q >> 2) * 16 + 4 * hq + (q & 3);
;         if (key <= myt) {
;           const uint32_t u32 = skey(sc[q]);
;           bool take, isc = false;
;           if (st0 == 0) take = (((unsigned long long)u32 << 16) | (unsigned long long)(8191 - key)) >= mytk;
;           else {
;             const uint32_t p16 = u32 >> 16;
;             take = p16 > (uint32_t)myp16;
;             isc = p16 == (uint32_t)myp16;
;           }
;           if (take) {
;             const int pos = atomicAdd(&cnt[mytok], 1);
;             if (pos < 256) sel[mytok * 256 + pos] = (unsigned short)key;
;           } else if (isc) {
;             const int pos = atomicAdd(&ccnt[mytok], 1);
;             if (pos < DSA_CAP) cand[mytok * 128 + pos] = ((unsigned long long)u32 << 16) | (unsigned long long)(8191 - key);
;           }
;         }
.Lcf_nc10:
	s_mov_b64 exec, s[2:3]
	v_cmp_lt_u32_e32 vcc, v219, v195
	s_mov_b64 exec, vcc
	s_cbranch_execz .Lcf_nc11
	v_lshrrev_b32_e32 v223, 16, v203
	v_subrev_u32_e32 v169, 17, v161
	v_lshl_or_b32 v222, v203, 16, v169
	v_lshl_add_u32 v167, v219, 3, v147
	ds_write_b64 v167, v[222:223] offset:16384
.Lcf_nc11:
	s_mov_b64 exec, s[2:3]
	v_cmp_lt_u32_e32 vcc, v220, v196
	s_mov_b64 exec, vcc
	s_cbranch_execz .Lcf_nc12
	v_lshrrev_b32_e32 v223, 16, v204
	v_subrev_u32_e32 v169, 18, v161
	v_lshl_or_b32 v222, v204, 16, v169
	v_lshl_add_u32 v167, v220, 3, v147
	ds_write_b64 v167, v[222:223] offset:16384
.Lcf_nc12:
	s_mov_b64 exec, s[2:3]
	v_cmp_lt_u32_e32 vcc, v221, v197
	s_mov_b64 exec, vcc
	s_cbranch_execz .Lcf_nc13
	v_lshrrev_b32_e32 v223, 16, v205
	v_subrev_u32_e32 v169, 19, v161
	v_lshl_or_b32 v222, v205, 16, v169
	v_lshl_add_u32 v167, v221, 3, v147
	ds_write_b64 v167, v[222:223] offset:16384
.Lcf_nc13:
	s_mov_b64 exec, s[2:3]
	s_branch .LBB0_1080
.Lcf_slow:
	s_and_saveexec_b64 s[2:3], s[60:61]
	s_cbranch_execz .LBB0_1094
	v_fma_f32 v0, |v94|, v128, v90
	v_fma_f32 v0, |v98|, v130, v0
	v_fma_f32 v0, |v102|, v132, v0
	v_fma_f32 v0, |v106|, v134, v0
	v_fma_f32 v0, |v110|, v136, v0
	v_fma_f32 v0, |v114|, v138, v0
	v_fma_f32 v0, |v118|, v140, v0
	v_fma_f32 v0, |v122|, v142, v0
	v_add_f32_e32 v0, 0, v0
	v_not_b32_e32 v90, v0
	v_or_b32_e32 v94, 0x80000000, v0
	v_cmp_gt_i32_e64 s[60:61], 0, v0
	s_nop 1
	v_cndmask_b32_e64 v0, v94, v90, s[60:61]
	s_and_saveexec_b64 s[14:15], s[46:47]
	s_xor_b64 s[14:15], exec, s[14:15]
	v_cmp_gt_u32_sdwa s[30:31], v0, v42 src0_sel:WORD_1 src1_sel:DWORD
	v_cmp_eq_u32_sdwa s[66:67], v0, v42 src0_sel:WORD_1 src1_sel:DWORD
	s_andn2_saveexec_b64 s[14:15], s[14:15]
	v_lshlrev_b64 v[164:165], 16, v[0:1]
	v_or_b32_e32 v164, v164, v161
	v_cmp_ge_u64_e64 s[60:61], v[164:165], v[44:45]
	s_andn2_b64 s[30:31], s[30:31], exec
	s_and_b64 s[60:61], s[60:61], exec
	s_andn2_b64 s[66:67], s[66:67], exec
	s_or_b64 s[30:31], s[30:31], s[60:61]
	s_or_b64 exec, exec, s[14:15]
	s_xor_b64 s[14:15], s[30:31], -1
	s_and_saveexec_b64 s[30:31], s[14:15]
	s_xor_b64 s[30:31], exec, s[30:31]
	s_cbranch_execz .LBB0_1091
	s_and_saveexec_b64 s[14:15], s[66:67]
	s_cbranch_execz .LBB0_1090
	ds_add_rtn_u32 v90, v145, v226 offset:41408
	s_waitcnt lgkmcnt(0)
	v_cmp_gt_i32_e64 s[60:61], s33, v90
	s_and_b64 exec, exec, s[60:61]
	v_lshlrev_b64 v[164:165], 16, v[0:1]
	v_or_b32_e32 v164, v164, v161
	v_lshl_add_u32 v0, v90, 3, v147
	ds_write_b64 v0, v[164:165] offset:16384
